# QKV/GU phase start: first-tile row-scale table computed after the first stage loads are in flight instead of before them
# speedup vs baseline: 1.0078x; 1.0037x over previous
; #define LAS __attribute__((address_space(3)))
; #define PG8_RTAB_FILL() do { if constexpr (Epi::ROWSCALE) { if (tid < 256) rtab[(ui & 1) * 256 + tid] = row_rstd(E.part, cur.pm * 256 + tid); } } while (0)
; __device__ __forceinline__ float row_rstd(const float* part, int row) {
;     const f32x4* p = (const f32x4*)(part + (size_t)row * NPART); f32x4 s = p[0];
; #pragma unroll
;     for (int i = 1; i < NPART / 4; ++i) s += p[i];
;     const float t = (s.x + s.y) + (s.z + s.w);
;     return __builtin_amdgcn_rsqf(t * (1.0f / DM) + RMS_EPS);
; }
; template <class Epi, bool ALIGN_EPI>
; __device__ __forceinline__ void gemm_phase(LAS unsigned char* lds, const Gemm g, int G, int cid, const Epi& E) {
;     ...
;     if (!S.next(0, cur)) return;
;     LAS float* rtab = (LAS float*)(lds + 8 * HTB);
;     ...
;     PG8_RTAB_FILL();
.LBB0_253:
	s_or_b64 exec, exec, s[28:29]
	v_readlane_b32 s0, v253, 13
	v_readlane_b32 s1, v253, 14
	s_mov_b32 s1, s31
	v_writelane_b32 v253, s0, 13
	v_mov_b32_e32 v187, v236
	s_nop 0
	v_writelane_b32 v253, s1, 14
	v_readlane_b32 s0, v254, 15
	v_readlane_b32 s1, v254, 16
	v_readlane_b32 s56, v253, 3
	v_readlane_b32 s58, v253, 5
	v_readlane_b32 s72, v253, 7
	s_andn2_b64 vcc, exec, s[0:1]
	v_readfirstlane_b32 s12, v187
	v_readlane_b32 s57, v253, 4
	v_readlane_b32 s59, v253, 6
	v_readlane_b32 s73, v253, 8
	s_cbranch_vccnz .LBB0_345
	s_movk_i32 s0, 0x100
	v_cmp_gt_i32_e64 s[38:39], s0, v187
	s_and_saveexec_b64 s[28:29], s[38:39]
	s_cbranch_execz .LBB0_256
	v_readlane_b32 s0, v255, 13
	s_nop 1
	v_add_u32_e32 v0, s0, v187
	v_ashrrev_i32_e32 v1, 31, v0
	v_lshlrev_b64 v[0:1], 7, v[0:1]
	v_lshl_add_u64 v[16:17], s[94:95], 0, v[0:1]
	global_load_dwordx4 v[40:43], v[16:17], off offset:48
	global_load_dwordx4 v[44:47], v[16:17], off offset:32
	global_load_dwordx4 v[48:51], v[16:17], off
	global_load_dwordx4 v[52:55], v[16:17], off offset:16
	global_load_dwordx4 v[56:59], v[16:17], off offset:112
	global_load_dwordx4 v[60:63], v[16:17], off offset:96
	global_load_dwordx4 v[64:67], v[16:17], off offset:80
	global_load_dwordx4 v[68:71], v[16:17], off offset:64

; #define PG8_STAGE(bufoff, gbase, voff) do { _Pragma("unroll") for (int _i = 0; _i < 2; ++_i) \
;         __builtin_amdgcn_global_load_lds((const unsigned*)((const char*)(gbase) + (voff)[_i]), (LAS unsigned*)(lds + (bufoff) + ldsw + _i * 8192), 16, 0, 0); } while (0)
; #define PG8_WAIT_V(n) asm volatile("s_waitcnt vmcnt(" #n ")" ::: "memory")
; #define PG8_BAR __builtin_amdgcn_s_barrier()
; __device__ __forceinline__ float row_rstd(const float* part, int row) {
;     const f32x4* p = (const f32x4*)(part + (size_t)row * NPART); f32x4 s = p[0];
; #pragma unroll
;     for (int i = 1; i < NPART / 4; ++i) s += p[i];
;     const float t = (s.x + s.y) + (s.z + s.w);
;     return __builtin_amdgcn_rsqf(t * (1.0f / DM) + RMS_EPS);
; }
; template <class Epi, bool ALIGN_EPI>
; __device__ __forceinline__ void gemm_phase(LAS unsigned char* lds, const Gemm g, int G, int cid, const Epi& E) {
;     ...
;     PG8_STAGE(PG8_SB(0, 0), cB, voffB); PG8_STAGE(PG8_SB(0, 1), cB + hB, voffB); PG8_STAGE(PG8_SA(0, 0), cA, voffA); PG8_STAGE(PG8_SA(0, 1), cA + hA, voffA);
;     if (wr == 1) PG8_BAR;
;     PG8_WAIT_V(2); PG8_BAR;
;     PG8_STAGE(PG8_SB(1, 0), cB + kB, voffB); PG8_STAGE(PG8_SA(1, 0), cA + kA, voffA); PG8_STAGE(PG8_SB(1, 1), cB + hB + kB, voffB);
;     PG8_WAIT_V(6); PG8_BAR;
.LBB0_258:
	s_and_b32 s6, s13, 3
	s_lshl_b32 s7, s30, 13
	s_lshl_b32 s77, s6, 5
	s_lshl_b32 s13, s6, 12
	s_add_u32 s40, s54, 0xc0000
	v_mov_b32_e32 v173, v139
	v_readlane_b32 s72, v255, 17
	s_addc_u32 s41, s55, 0
	v_mov_b32_e32 v177, v139
	v_mov_b32_e32 v137, v139
	v_readlane_b32 s73, v255, 18
	s_add_i32 m0, s23, 0x18000
	v_lshl_add_u64 v[12:13], s[40:41], 0, v[172:173]
	v_lshl_add_u64 v[8:9], s[72:73], 0, v[136:137]
	v_mov_b32_e32 v175, v139
	s_waitcnt vmcnt(2)
	s_and_saveexec_b64 vcc, s[38:39]
	s_cbranch_execz .Lrt_skip_qkv
	v_pk_add_f32 v[50:51], v[50:51], v[54:55]
	v_pk_add_f32 v[48:49], v[48:49], v[52:53]
	v_pk_add_f32 v[46:47], v[50:51], v[46:47]
	v_pk_add_f32 v[44:45], v[48:49], v[44:45]
	v_pk_add_f32 v[72:73], v[46:47], v[42:43]
	v_pk_add_f32 v[74:75], v[44:45], v[40:41]
	v_pk_add_f32 v[70:71], v[72:73], v[70:71]
	v_pk_add_f32 v[68:69], v[74:75], v[68:69]
	v_pk_add_f32 v[66:67], v[70:71], v[66:67]
	v_pk_add_f32 v[64:65], v[68:69], v[64:65]
	v_pk_add_f32 v[62:63], v[66:67], v[62:63]
	v_pk_add_f32 v[60:61], v[64:65], v[60:61]
	v_pk_add_f32 v[58:59], v[62:63], v[58:59]
	v_pk_add_f32 v[56:57], v[60:61], v[56:57]
	s_nop 0
	v_pk_mov_b32 v[60:61], v[56:57], v[58:59] op_sel:[1,0]
	v_mov_b32_e32 v57, v59
	v_pk_add_f32 v[56:57], v[60:61], v[56:57]
	s_nop 0
	v_add_f32_e32 v56, v56, v57
	v_fmamk_f32 v56, v56, 0x3a000000, v237
	v_rsq_f32_e32 v56, v56
	v_lshl_add_u32 v57, v187, 2, 0
	v_add_u32_e32 v57, 0x20000, v57
	ds_write_b32 v57, v56
.Lrt_skip_qkv:
	s_or_b64 exec, exec, vcc
	s_barrier
	global_load_lds_dwordx4 v[12:13], off
	v_lshl_add_u64 v[12:13], s[40:41], 0, v[176:177]
	s_add_i32 m0, s23, 0x1a000
	s_add_i32 s78, s23, 0x8000
	s_add_i32 s79, s23, 0xa000
	v_lshl_add_u64 v[10:11], s[72:73], 0, v[174:175]
	global_load_lds_dwordx4 v[12:13], off
	v_lshl_add_u64 v[8:9], v[8:9], 0, s[36:37]
	s_mov_b32 m0, s78
	s_add_u32 s40, s54, 0xc2000
	global_load_lds_dwordx4 v[8:9], off
	v_lshl_add_u64 v[8:9], v[10:11], 0, s[36:37]
	s_mov_b32 m0, s79
	s_addc_u32 s41, s55, 0
	global_load_lds_dwordx4 v[8:9], off
	s_add_i32 m0, s23, 0x1c000
	v_lshl_add_u64 v[8:9], s[40:41], 0, v[172:173]
	global_load_lds_dwordx4 v[8:9], off
	v_lshl_add_u64 v[8:9], s[40:41], 0, v[176:177]
	s_add_i32 m0, s23, 0x1e000
	v_bfe_u32 v10, v187, 4, 2
	global_load_lds_dwordx4 v[8:9], off
	v_and_b32_e32 v9, 15, v187
	v_lshlrev_b32_e32 v11, 4, v10
	v_lshl_or_b32 v189, s30, 6, v9
	v_lshl_or_b32 v9, v9, 6, v11
	v_lshlrev_b32_e32 v11, 2, v187
	v_and_b32_e32 v12, 32, v11
	v_bitop3_b32 v13, v9, s7, v12 bitop3:0xde
	s_add_i32 s7, 0, 0x20000
	s_cmpk_lt_u32 s12, 0x100
	v_add_u32_e32 v191, s7, v11
	s_cselect_b64 s[46:47], -1, 0
	s_lshl_b32 s7, s6, 7
	s_add_i32 s7, s7, 0
	s_add_i32 s7, s7, 0x22800
	v_lshl_add_u32 v197, v10, 5, s7
	v_readlane_b32 s7, v253, 0
	s_lshl_b32 s6, s6, 2
	v_bitop3_b32 v190, v9, s13, v12 bitop3:0xde
	v_lshl_add_u32 v206, v189, 5, s7
	v_add_u32_e32 v208, 0x200, v206
	v_add_u32_e32 v210, 0x400, v206
	v_add_u32_e32 v212, 0x600, v206
	v_add_u32_e32 v214, 0x1000, v206
	v_add_u32_e32 v216, 0x1200, v206
	v_add_u32_e32 v218, 0x1400, v206
	v_add_u32_e32 v220, 0x1600, v206
	v_add_u32_e32 v207, s6, v206
	v_add_u32_e32 v209, s6, v208
	v_add_u32_e32 v211, s6, v210
	v_add_u32_e32 v213, s6, v212
	v_add_u32_e32 v215, s6, v214
	v_add_u32_e32 v217, s6, v216
	v_add_u32_e32 v219, s6, v218
	v_add_u32_e32 v221, s6, v220
	s_movk_i32 s6, 0x840
	v_lshrrev_b32_e32 v9, 1, v0
	v_mul_lo_u32 v0, v2, s6
	s_mov_b32 s7, 0x8400
	v_lshlrev_b32_e32 v8, 3, v10
	v_cmp_eq_u32_e64 s[40:41], 0, v10
	v_mad_u64_u32 v[10:11], s[12:13], v9, s7, v[0:1]
	v_or_b32_e32 v0, v10, v1
	v_add_lshl_u32 v138, v0, v3, 1
	v_lshrrev_b32_e32 v1, 1, v4
	v_mul_lo_u32 v0, v6, s6
	v_mad_u64_u32 v[0:1], s[12:13], v1, s7, v[0:1]
	s_waitcnt vmcnt(6)
	s_mov_b64 s[42:43], 0x84080
	v_or_b32_e32 v0, v0, v5
	v_lshl_add_u64 v[178:179], v[138:139], 0, s[42:43]
	v_add_lshl_u32 v138, v0, v7, 1
	s_mov_b32 s91, 0
	v_lshl_add_u64 v[180:181], v[138:139], 0, s[42:43]
	v_add_u32_e32 v222, 0, v13
	v_lshlrev_b32_e32 v138, 1, v8
	v_readlane_b32 s12, v255, 12
	v_readlane_b32 s13, v255, 14
	s_barrier
	s_branch .LBB0_261

; #define LAS __attribute__((address_space(3)))
; #define PG8_RTAB_FILL() do { if constexpr (Epi::ROWSCALE) { if (tid < 256) rtab[(ui & 1) * 256 + tid] = row_rstd(E.part, cur.pm * 256 + tid); } } while (0)
; __device__ __forceinline__ float row_rstd(const float* part, int row) {
;     const f32x4* p = (const f32x4*)(part + (size_t)row * NPART); f32x4 s = p[0];
; #pragma unroll
;     for (int i = 1; i < NPART / 4; ++i) s += p[i];
;     const float t = (s.x + s.y) + (s.z + s.w);
;     return __builtin_amdgcn_rsqf(t * (1.0f / DM) + RMS_EPS);
; }
; template <class Epi, bool ALIGN_EPI>
; __device__ __forceinline__ void gemm_phase(LAS unsigned char* lds, const Gemm g, int G, int cid, const Epi& E) {
;     ...
;     if (!S.next(0, cur)) return;
;     LAS float* rtab = (LAS float*)(lds + 8 * HTB);
;     ...
;     PG8_RTAB_FILL();
.LBB0_800:
	v_readlane_b32 s0, v254, 57
	v_mov_b32_e32 v174, v236
	v_readlane_b32 s1, v254, 58
	s_mul_hi_u32 s72, s90, 0x2c00000
	s_mul_i32 s73, s90, 0x2c00000
	s_and_b64 vcc, exec, s[0:1]
	v_readfirstlane_b32 s28, v174
	s_cbranch_vccz .LBB0_826
	s_movk_i32 s0, 0x100
	v_cmp_gt_i32_e64 s[38:39], s0, v174
	s_and_saveexec_b64 s[22:23], s[38:39]
	s_cbranch_execz .LBB0_803
	v_readlane_b32 s0, v254, 60
	s_nop 1
	v_add_u32_e32 v0, s0, v174
	s_waitcnt lgkmcnt(0)
	v_ashrrev_i32_e32 v1, 31, v0
	v_lshlrev_b64 v[0:1], 7, v[0:1]
	v_lshl_add_u64 v[16:17], s[94:95], 0, v[0:1]
	global_load_dwordx4 v[40:43], v[16:17], off offset:48
	global_load_dwordx4 v[44:47], v[16:17], off offset:32
	global_load_dwordx4 v[48:51], v[16:17], off
	global_load_dwordx4 v[52:55], v[16:17], off offset:16
	global_load_dwordx4 v[56:59], v[16:17], off offset:112
	global_load_dwordx4 v[60:63], v[16:17], off offset:96
	global_load_dwordx4 v[64:67], v[16:17], off offset:80
	global_load_dwordx4 v[68:71], v[16:17], off offset:64

; #define PG8_STAGE(bufoff, gbase, voff) do { _Pragma("unroll") for (int _i = 0; _i < 2; ++_i) \
;         __builtin_amdgcn_global_load_lds((const unsigned*)((const char*)(gbase) + (voff)[_i]), (LAS unsigned*)(lds + (bufoff) + ldsw + _i * 8192), 16, 0, 0); } while (0)
; #define PG8_WAIT_V(n) asm volatile("s_waitcnt vmcnt(" #n ")" ::: "memory")
; #define PG8_BAR __builtin_amdgcn_s_barrier()
; __device__ __forceinline__ float row_rstd(const float* part, int row) {
;     const f32x4* p = (const f32x4*)(part + (size_t)row * NPART); f32x4 s = p[0];
; #pragma unroll
;     for (int i = 1; i < NPART / 4; ++i) s += p[i];
;     const float t = (s.x + s.y) + (s.z + s.w);
;     return __builtin_amdgcn_rsqf(t * (1.0f / DM) + RMS_EPS);
; }
; template <class Epi, bool ALIGN_EPI>
; __device__ __forceinline__ void gemm_phase(LAS unsigned char* lds, const Gemm g, int G, int cid, const Epi& E) {
;     ...
;     PG8_STAGE(PG8_SB(0, 0), cB, voffB); PG8_STAGE(PG8_SB(0, 1), cB + hB, voffB); PG8_STAGE(PG8_SA(0, 0), cA, voffA); PG8_STAGE(PG8_SA(0, 1), cA + hA, voffA);
;     if (wr == 1) PG8_BAR;
;     PG8_WAIT_V(2); PG8_BAR;
;     PG8_STAGE(PG8_SB(1, 0), cB + kB, voffB); PG8_STAGE(PG8_SA(1, 0), cA + kA, voffA); PG8_STAGE(PG8_SB(1, 1), cB + hB + kB, voffB);
;     PG8_WAIT_V(6); PG8_BAR;
.LBB0_805:
	s_add_u32 s6, s50, 0x160000
	v_lshrrev_b32_e32 v12, 1, v174
	s_addc_u32 s7, s51, 0
	v_and_b32_e32 v12, 24, v12
	s_add_u32 s40, s50, 0x162000
	v_and_b32_e32 v13, 15, v174
	v_lshlrev_b32_e32 v14, 1, v12
	s_addc_u32 s41, s51, 0
	v_lshl_or_b32 v175, s29, 6, v13
	v_lshl_or_b32 v14, v13, 6, v14
	v_lshlrev_b32_e32 v13, 2, v13
	s_lshl_b32 s30, s30, 5
	s_lshl_b32 s42, s29, 13
	v_and_b32_e32 v15, 32, v13
	s_and_b32 s30, s30, 0x60
	v_mov_b32_e32 v165, v139
	v_readlane_b32 s52, v255, 0
	v_bitop3_b32 v16, v14, s42, v15 bitop3:0xde
	s_lshl_b32 s42, s30, 7
	v_mov_b32_e32 v169, v139
	v_mov_b32_e32 v137, v139
	v_readlane_b32 s53, v255, 1
	v_bitop3_b32 v176, v14, s42, v15 bitop3:0xde
	s_add_i32 m0, s13, 0x18000
	v_lshl_add_u64 v[14:15], s[6:7], 0, v[164:165]
	v_lshl_add_u64 v[8:9], s[52:53], 0, v[136:137]
	v_mov_b32_e32 v167, v139
	s_waitcnt vmcnt(2)
	s_and_saveexec_b64 vcc, s[38:39]
	s_cbranch_execz .Lrt_skip_gu
	v_pk_add_f32 v[50:51], v[50:51], v[54:55]
	v_pk_add_f32 v[48:49], v[48:49], v[52:53]
	v_pk_add_f32 v[46:47], v[50:51], v[46:47]
	v_pk_add_f32 v[44:45], v[48:49], v[44:45]
	v_pk_add_f32 v[72:73], v[46:47], v[42:43]
	v_pk_add_f32 v[74:75], v[44:45], v[40:41]
	v_pk_add_f32 v[70:71], v[72:73], v[70:71]
	v_pk_add_f32 v[68:69], v[74:75], v[68:69]
	v_pk_add_f32 v[66:67], v[70:71], v[66:67]
	v_pk_add_f32 v[64:65], v[68:69], v[64:65]
	v_pk_add_f32 v[62:63], v[66:67], v[62:63]
	v_pk_add_f32 v[60:61], v[64:65], v[60:61]
	v_pk_add_f32 v[58:59], v[62:63], v[58:59]
	v_pk_add_f32 v[56:57], v[60:61], v[56:57]
	s_nop 0
	v_pk_mov_b32 v[60:61], v[56:57], v[58:59] op_sel:[1,0]
	v_mov_b32_e32 v57, v59
	v_pk_add_f32 v[56:57], v[60:61], v[56:57]
	s_nop 0
	v_add_f32_e32 v56, v56, v57
	v_fmamk_f32 v56, v56, 0x3a000000, v237
	v_rsq_f32_e32 v56, v56
	v_lshl_add_u32 v57, v174, 2, 0
	v_add_u32_e32 v57, 0x20000, v57
	ds_write_b32 v57, v56
.Lrt_skip_gu:
	s_or_b64 exec, exec, vcc
	s_barrier
	global_load_lds_dwordx4 v[14:15], off
	v_lshl_add_u64 v[14:15], s[6:7], 0, v[168:169]
	s_add_i32 m0, s13, 0x1a000
	s_add_i32 s75, s13, 0x8000
	v_lshl_add_u64 v[10:11], s[52:53], 0, v[166:167]
	global_load_lds_dwordx4 v[14:15], off
	v_lshl_add_u64 v[8:9], v[8:9], 0, s[36:37]
	s_mov_b32 m0, s75
	s_add_i32 s76, s13, 0xa000
	global_load_lds_dwordx4 v[8:9], off
	v_lshl_add_u64 v[8:9], v[10:11], 0, s[36:37]
	s_mov_b32 m0, s76
	s_lshl_b32 s6, s29, 8
	global_load_lds_dwordx4 v[8:9], off
	s_add_i32 m0, s13, 0x1c000
	v_lshl_add_u64 v[8:9], s[40:41], 0, v[164:165]
	global_load_lds_dwordx4 v[8:9], off
	v_lshl_add_u64 v[8:9], s[40:41], 0, v[168:169]
	s_add_i32 m0, s13, 0x1e000
	s_add_i32 s7, 0, 0x20000
	global_load_lds_dwordx4 v[8:9], off
	s_movk_i32 s40, 0x840
	s_add_i32 s6, s7, s6
	v_lshrrev_b32_e32 v8, 1, v0
	v_mul_lo_u32 v0, v2, s40
	s_mov_b32 s41, 0x8400
	v_add_u32_e32 v177, s6, v13
	v_lshl_add_u32 v178, v174, 2, s7
	v_mad_u64_u32 v[8:9], s[6:7], v8, s41, v[0:1]
	v_or_b32_e32 v0, v8, v1
	v_add_lshl_u32 v138, v0, v3, 1
	v_lshrrev_b32_e32 v1, 1, v4
	v_mul_lo_u32 v0, v6, s40
	v_mad_u64_u32 v[0:1], s[6:7], v1, s41, v[0:1]
	s_waitcnt vmcnt(6)
	s_mov_b64 s[42:43], 0x84080
	v_or_b32_e32 v0, v0, v5
	s_cmpk_lt_u32 s28, 0x100
	v_lshl_add_u64 v[170:171], v[138:139], 0, s[42:43]
	v_add_lshl_u32 v138, v0, v7, 1
	s_cselect_b64 s[28:29], -1, 0
	v_lshl_add_u64 v[172:173], v[138:139], 0, s[42:43]
	s_mov_b32 s90, 0
	v_add_u32_e32 v179, 0, v16
	s_lshl_b32 s30, s30, 1
	v_lshlrev_b32_e32 v138, 1, v12
	v_readlane_b32 s86, v254, 59
	v_readlane_b32 s87, v254, 61
	s_barrier
	s_branch .LBB0_808
